# attnA item start no longer drains the previous item's stores before issuing its Q / first-tile loads
# speedup vs baseline: 1.0047x; 1.0001x over previous
; DI int ltid_w(int wave) { int t; asm volatile("v_mbcnt_lo_u32_b32 %0, -1, 0\n\tv_mbcnt_hi_u32_b32 %0, -1, %0" : "=v"(t)); return (wave << 6) | t; }
; template <int MODE>
; DI void attn_mfma(const Params& p, int l, int b, int hd, int qb, unsigned char* smem) {
;     ...
;   const int tid = ltid_w(p.wave), lane = tid & 63, wv = tid >> 6, r = lane & 31, h2 = lane >> 5;
;   const int mp = MODE ? 0 : (wv >> 1);
;   const bf16_t* P = (const bf16_t*)(p.ws + WS_P);
;   bf16_t* MIX = (bf16_t*)(p.ws + WS_HM);
;   const int kvh = MODE ? (hd >> 1) : hd;
;   const bf16_t* VT = MODE ? (const bf16_t*)(p.ws + WS_VTC) + ((size_t)(b * 2 + kvh) * 64) * NTOK : (const bf16_t*)(p.ws + WS_VTA) + ((size_t)(b * 4 + hd) * 64) * NTOK;
;   const int qcol = MODE ? C_Q + hd * 64 : A_Q + hd * 64;
;   const int kcol = MODE ? C_K + kvh * 64 : A_K + hd * 64;
;   unsigned char* sK = smem;
;   unsigned char* sV = smem + 8192;
;   const int tq = qb * QPB + (MODE ? wv : (wv & 1)) * 32 + r;
;   const size_t qrow = (size_t)b * NTOK + tq;
;   bf16x8 qf[KS];
; #pragma unroll
;   for (int ks = 0; ks < KS; ++ks) qf[ks] = *(const bf16x8*)(P + qrow * PW + qcol + (2 * (mp * 2 + ks) + h2) * 8);
;   const bool isctx = qb * QPB < NCTX;
;   int ntiles, band_lo = 0;
;   if (MODE == 0) ntiles = isctx ? 4 : 36;
;   else {
;     if (isctx) ntiles = 4;
;     else { const int i0 = qb * QPB - NCTX; int lo = i0 - 128; if (lo < 0) lo = 0; int hi = i0 + 256; if (hi > NLAT) hi = NLAT; band_lo = lo; ntiles = 4 + (hi - lo) / 64; }
;   }
;   const float cexp = (MODE ? 0.125f : 0.17677669529663687f) * 1.4426950408889634f;
;   float mrun = MODE ? p.sw_sink[l * 4 + hd] * 1.4426950408889634f : -1e30f;
;   float lsum = (MODE && h2 == 0) ? 1.f : 0.f;
;   f32x16 O[2];
; #pragma unroll
;   for (int vt = 0; vt < 2; ++vt)
; #pragma unroll
;     for (int i = 0; i < 16; ++i) O[vt][i] = 0.f;
;   const int lrow = tid >> 3, lc = tid & 7;
;   auto tile_base = [&](int j) -> int { return (MODE == 0 || j < 4) ? j * 64 : NCTX + band_lo + (j - 4) * 64; };
;   uint4 gk00, gk01, gk10, gk11, gv00, gv01, gv10, gv11;
;     ...
;   ATT_LOAD(tile_base(0), gk00, gk01, gv00, gv01);
;   ATT_LOAD(tile_base(1), gk10, gk11, gv10, gv11);
.LBB0_575:
	s_andn2_b64 vcc, exec, s[0:1]
	s_cbranch_vccnz .LBB0_591
	s_add_i32 s0, s46, 0xffc0
	s_and_b32 s8, s0, 0xffff
	s_mul_i32 s1, s8, 0xe38f
	s_lshr_b32 s5, s1, 21
	s_mul_i32 s1, s5, 36
	s_sub_i32 s2, s0, s1
	s_and_b32 s0, s2, 0xffff
	s_cmp_lt_u32 s0, 4
	v_readlane_b32 s6, v254, 12
	s_cselect_b64 s[0:1], -1, 0
	v_readlane_b32 s7, v254, 13
	s_and_b64 s[6:7], s[6:7], s[0:1]
	s_and_b64 vcc, exec, s[6:7]
	s_cbranch_vccnz .LBB0_591
	s_and_b32 s4, 0xffff, s5
	s_lshr_b32 s9, s4, 2
	s_and_b32 s6, s4, 3
	v_readlane_b32 s4, v253, 39
	s_add_u32 s10, s40, 0x41c6000
	v_mbcnt_lo_u32_b32 v6, -1, 0
	v_mbcnt_hi_u32_b32 v6, -1, v6
	s_addc_u32 s11, s41, 0
	v_or_b32_e32 v196, s4, v6
	s_lshl_b32 s4, s9, 8
	s_lshl_b32 s7, s6, 6
	s_or_b32 s4, s7, s4
	s_mulk_i32 s4, 0x1200
	s_add_u32 s4, s40, s4
	s_addc_u32 s13, s41, 0
	s_add_u32 s12, s4, 0xef06000
	s_addc_u32 s13, s13, 0
	s_lshl_b32 s2, s2, 6
	s_and_b32 s2, s2, 0xffc0
	v_lshrrev_b32_e32 v0, 1, v196
	s_mul_i32 s14, s9, 0x900
	v_and_b32_e32 v198, 31, v6
	v_and_b32_e32 v199, 32, v0
	s_add_i32 s2, s14, s2
	v_bfe_u32 v171, v6, 5, 1
	v_or3_b32 v165, v198, s2, v199
	v_ashrrev_i32_e32 v197, 7, v196
	v_mul_lo_u32 v160, v165, s33
	v_lshlrev_b32_e32 v164, 3, v171
	v_lshl_add_u64 v[166:167], s[10:11], 0, v[160:161]
	s_lshl_b32 s2, s6, 7
	v_lshl_or_b32 v2, v197, 5, v164
	v_lshl_add_u64 v[0:1], v[166:167], 0, s[2:3]
	v_ashrrev_i32_e32 v3, 31, v2
	v_lshl_add_u64 v[0:1], v[2:3], 1, v[0:1]
	v_ashrrev_i32_e32 v8, 3, v196
	s_nop 0
	global_load_dwordx4 v[96:99], v[0:1], off
	global_load_dwordx4 v[100:103], v[0:1], off offset:32
	v_add_u32_e32 v7, s14, v8
	v_mov_b64_e32 v[0:1], s[10:11]
	v_lshlrev_b32_e32 v9, 4, v6
	s_and_b64 s[0:1], s[0:1], exec
	v_mad_i64_i32 v[2:3], s[0:1], v7, s33, v[0:1]
	v_and_b32_e32 v160, 0x70, v9
	s_cselect_b32 s4, 4, 36
	v_lshl_add_u64 v[4:5], v[2:3], 0, s[2:3]
	v_lshl_add_u64 v[2:3], v[2:3], 0, v[160:161]
	s_or_b32 s0, s2, 0x200
	s_mov_b32 s1, s3
	v_lshl_add_u64 v[2:3], v[2:3], 0, s[0:1]
	s_mov_b32 s14, 0x44000
	v_add_co_u32_e32 v2, vcc, s14, v2
	v_lshl_add_u64 v[4:5], v[4:5], 0, v[160:161]
	s_nop 0
	v_addc_co_u32_e32 v3, vcc, 0, v3, vcc
	global_load_dwordx4 v[104:107], v[4:5], off offset:512
	global_load_dwordx4 v[108:111], v[2:3], off offset:1024
	v_mov_b64_e32 v[2:3], s[12:13]
	v_add_u32_e32 v6, 32, v8
	v_mad_i64_i32 v[4:5], s[10:11], v8, s67, v[2:3]
	v_mad_i64_i32 v[2:3], s[10:11], v6, s67, v[2:3]
	v_add_u32_e32 v6, 64, v7
	v_mad_i64_i32 v[0:1], s[10:11], v6, s33, v[0:1]
	v_lshl_add_u64 v[6:7], v[0:1], 0, s[2:3]
	v_lshl_add_u64 v[0:1], v[0:1], 0, v[160:161]
	v_lshl_add_u64 v[0:1], v[0:1], 0, s[0:1]
	v_lshl_add_u64 v[6:7], v[6:7], 0, v[160:161]
	v_add_co_u32_e32 v0, vcc, s14, v0
	v_lshl_add_u64 v[4:5], v[4:5], 0, v[160:161]
	v_lshl_add_u64 v[2:3], v[2:3], 0, v[160:161]
	v_addc_co_u32_e32 v1, vcc, 0, v1, vcc
	global_load_dwordx4 v[112:115], v[6:7], off offset:512
	global_load_dwordx4 v[116:119], v[0:1], off offset:1024
	global_load_dwordx4 v[120:123], v[4:5], off
	global_load_dwordx4 v[124:127], v[4:5], off offset:128
	global_load_dwordx4 v[128:131], v[2:3], off
	global_load_dwordx4 v[132:135], v[2:3], off offset:128
	s_movk_i32 s0, 0x70
	v_bitop3_b32 v0, v196, s0, v9 bitop3:0x48
	s_movk_i32 s0, 0x88
	v_mul_lo_u32 v2, v8, s0
	s_mul_i32 s0, s9, 0x90000
	s_mul_i32 s1, s6, 0x24000
	s_add_i32 s0, s0, s1
	v_lshlrev_b32_e32 v1, 2, v197
	v_bfe_u32 v4, v196, 1, 3
	s_lshl_b32 s0, s0, 1
	v_lshl_or_b32 v141, v8, 7, v0
	v_lshlrev_b32_e32 v0, 7, v198
	v_or_b32_e32 v3, v1, v171
	v_bitop3_b32 v1, v1, v4, v171 bitop3:0x36
	s_add_u32 s0, s40, s0
	v_lshl_add_u32 v142, v1, 4, v0
	v_bitop3_b32 v1, v3, v4, 2 bitop3:0x36
	s_addc_u32 s1, s41, 0
	v_lshl_add_u32 v143, v1, 4, v0
	v_mov_b64_e32 v[0:1], s[0:1]
	s_and_b32 s5, s5, 3
	v_mbcnt_hi_u32_b32 v5, -1, v185
	v_mad_i64_i32 v[136:137], s[0:1], v8, s67, v[0:1]
	s_lshl_b32 s5, s5, 7
	v_and_b32_e32 v7, 64, v5
	s_mul_hi_u32 s0, s8, 0x1c71c72
	s_add_u32 s5, s40, s5
	v_xor_b32_e32 v6, 32, v5
	v_add_u32_e32 v7, 64, v7
	s_mul_hi_u32 s1, s0, 0x1332000
	s_mul_i32 s0, s0, 0x1332000
	s_addc_u32 s8, s41, 0
	v_cmp_lt_i32_e32 vcc, v6, v7
	s_add_u32 s0, s5, s0
	s_addc_u32 s1, s8, s1
	v_cndmask_b32_e32 v5, v5, v6, vcc
	v_lshlrev_b32_e32 v170, 2, v5
	v_mul_u32_u24_e32 v5, 0x88, v198
	v_mov_b64_e32 v[0:1], s[0:1]
	v_mov_b32_e32 v200, 0
	s_mov_b32 s2, 0
	v_mad_i64_i32 v[138:139], s[0:1], v8, s33, v[0:1]
	v_mov_b32_e32 v140, 0xf149f2ca
	v_add_u32_e32 v144, v2, v160
	v_add_u32_e32 v145, v164, v5
	v_add_u32_e32 v236, 0x2000, v145
	v_add_u32_e32 v237, 0x3000, v145
	v_add_u32_e32 v238, 0x6000, v145
	v_add_u32_e32 v239, 0x7000, v145
	v_mov_b32_e32 v16, 0
	v_mov_b32_e32 v17, v200
	v_mov_b32_e32 v18, v200
	v_mov_b32_e32 v19, v200
	v_mov_b32_e32 v20, v200
	v_mov_b32_e32 v21, v200
	v_mov_b32_e32 v22, v200
	v_mov_b32_e32 v23, v200
	v_mov_b32_e32 v24, v200
	v_mov_b32_e32 v25, v200
	v_mov_b32_e32 v26, v200
	v_mov_b32_e32 v27, v200
	v_mov_b32_e32 v28, v200
	v_mov_b32_e32 v29, v200
	v_mov_b32_e32 v30, v200
	v_mov_b32_e32 v31, v200
	v_mov_b32_e32 v0, v200
	v_mov_b32_e32 v1, v200
	v_mov_b32_e32 v2, v200
	v_mov_b32_e32 v3, v200
	v_mov_b32_e32 v4, v200
	v_mov_b32_e32 v5, v200
	v_mov_b32_e32 v6, v200
	v_mov_b32_e32 v7, v200
	v_mov_b32_e32 v8, v200
	v_mov_b32_e32 v9, v200
	v_mov_b32_e32 v10, v200
	v_mov_b32_e32 v11, v200
	v_mov_b32_e32 v12, v200
	v_mov_b32_e32 v13, v200
	v_mov_b32_e32 v14, v200
	v_mov_b32_e32 v15, v200
	s_branch .LBB0_580
